# FFN-in GEMM phase rewritten by hand: 256x128 workgroup tile, single LDS stage, AGPR B fragments, paired bf16 stores
# speedup vs baseline: 1.0750x; 1.0067x over previous
.Lfi_entry:
	v_and_b32_e32 v225, 63, v170
	v_lshrrev_b32_e32 v226, 6, v170
	v_lshrrev_b32_e32 v227, 1, v226
	v_and_b32_e32 v228, 1, v226
	v_and_b32_e32 v229, 15, v225
	v_lshrrev_b32_e32 v230, 4, v225
	v_lshlrev_b32_e32 v231, 10, v226
	v_lshrrev_b32_e32 v232, 3, v170
	v_readfirstlane_b32 s52, v231
	v_and_b32_e32 v233, 7, v170
	v_bfe_u32 v224, v232, 1, 3
	v_xor_b32_e32 v233, v233, v224
	v_lshlrev_b32_e32 v233, 4, v233
	s_movk_i32 s4, 0x880
	v_mad_u32_u24 v224, v232, s4, v233
	v_lshrrev_b32_e32 v232, 3, v170
	v_and_b32_e32 v233, 15, v232
	v_lshlrev_b32_e32 v233, 1, v233
	v_lshrrev_b32_e32 v168, 4, v232
	v_add_u32_e32 v233, v233, v168
	v_and_b32_e32 v168, 7, v170
	v_bfe_u32 v169, v232, 1, 3
	v_xor_b32_e32 v168, v168, v169
	v_lshlrev_b32_e32 v168, 4, v168
	v_mad_u32_u24 v168, v233, s4, v168
	v_bfe_u32 v233, v229, 1, 3
	v_xor_b32_e32 v231, v230, v233
	v_or_b32_e32 v232, 4, v230
	v_xor_b32_e32 v232, v232, v233
	v_lshlrev_b32_e32 v231, 4, v231
	v_lshlrev_b32_e32 v232, 4, v232
	v_lshl_add_u32 v233, v227, 7, v229
	v_lshlrev_b32_e32 v233, 7, v233
	v_add_u32_e32 v220, v233, v231
	v_add_u32_e32 v221, v233, v232
	v_lshl_add_u32 v233, v228, 6, v229
	v_lshlrev_b32_e32 v233, 7, v233
	v_add_u32_e32 v233, 0x8000, v233
	v_add_u32_e32 v222, v233, v231
	v_add_u32_e32 v223, v233, v232
	v_lshlrev_b32_e32 v231, 7, v227
	v_lshl_add_u32 v231, v230, 2, v231
	s_movk_i32 s4, 0x1680
	v_lshlrev_b32_e32 v232, 4, v228
	v_add_u32_e32 v232, v232, v229
	v_lshlrev_b32_e32 v232, 2, v232
	v_mad_u32_u24 v225, v231, s4, v232
	v_readlane_b32 s54, v237, 0
.Lfi_tile:
	s_cmp_ge_u32 s54, 2112
	s_cbranch_scc1 .Lfi_done
	s_lshr_b32 s55, s54, 4
	s_mul_hi_u32 s55, s55, 0x55555556
	s_mul_i32 s53, s55, 48
	s_sub_u32 s53, s54, s53
	v_readlane_b32 s4, v235, 34
	v_readlane_b32 s5, v235, 35
	s_mul_i32 s44, s53, 0x88000
	s_add_u32 s44, s44, 0xe166000
	s_add_u32 s44, s44, s4
	s_addc_u32 s45, s5, 0
	s_mul_i32 s46, s55, 0x44000
	s_add_u32 s46, s46, s36
	s_addc_u32 s47, s37, 0
	s_mul_i32 s50, s53, 0x168000
	s_lshl_b32 s55, s55, 7
	s_add_u32 s50, s50, s55
	s_add_u32 s50, s50, 0xfae6000
	s_add_u32 s50, s50, s4
	s_addc_u32 s51, s5, 0
	v_mov_b32_e32 v0, 0
	v_mov_b32_e32 v1, 0
	v_mov_b32_e32 v2, 0
	v_mov_b32_e32 v3, 0
	v_mov_b32_e32 v4, 0
	v_mov_b32_e32 v5, 0
	v_mov_b32_e32 v6, 0
	v_mov_b32_e32 v7, 0
	v_mov_b32_e32 v8, 0
	v_mov_b32_e32 v9, 0
	v_mov_b32_e32 v10, 0
	v_mov_b32_e32 v11, 0
	v_mov_b32_e32 v12, 0
	v_mov_b32_e32 v13, 0
	v_mov_b32_e32 v14, 0
	v_mov_b32_e32 v15, 0
	v_mov_b32_e32 v16, 0
	v_mov_b32_e32 v17, 0
	v_mov_b32_e32 v18, 0
	v_mov_b32_e32 v19, 0
	v_mov_b32_e32 v20, 0
	v_mov_b32_e32 v21, 0
	v_mov_b32_e32 v22, 0
	v_mov_b32_e32 v23, 0
	v_mov_b32_e32 v24, 0
	v_mov_b32_e32 v25, 0
	v_mov_b32_e32 v26, 0
	v_mov_b32_e32 v27, 0
	v_mov_b32_e32 v28, 0
	v_mov_b32_e32 v29, 0
	v_mov_b32_e32 v30, 0
	v_mov_b32_e32 v31, 0
	v_mov_b32_e32 v32, 0
	v_mov_b32_e32 v33, 0
	v_mov_b32_e32 v34, 0
	v_mov_b32_e32 v35, 0
	v_mov_b32_e32 v36, 0
	v_mov_b32_e32 v37, 0
	v_mov_b32_e32 v38, 0
	v_mov_b32_e32 v39, 0
	v_mov_b32_e32 v40, 0
	v_mov_b32_e32 v41, 0
	v_mov_b32_e32 v42, 0
	v_mov_b32_e32 v43, 0
	v_mov_b32_e32 v44, 0
	v_mov_b32_e32 v45, 0
	v_mov_b32_e32 v46, 0
	v_mov_b32_e32 v47, 0
	v_mov_b32_e32 v48, 0
	v_mov_b32_e32 v49, 0
	v_mov_b32_e32 v50, 0
	v_mov_b32_e32 v51, 0
	v_mov_b32_e32 v52, 0
	v_mov_b32_e32 v53, 0
	v_mov_b32_e32 v54, 0
	v_mov_b32_e32 v55, 0
	v_mov_b32_e32 v56, 0
	v_mov_b32_e32 v57, 0
	v_mov_b32_e32 v58, 0
	v_mov_b32_e32 v59, 0
	v_mov_b32_e32 v60, 0
	v_mov_b32_e32 v61, 0
	v_mov_b32_e32 v62, 0
	v_mov_b32_e32 v63, 0
	v_mov_b32_e32 v64, 0
	v_mov_b32_e32 v65, 0
	v_mov_b32_e32 v66, 0
	v_mov_b32_e32 v67, 0
	v_mov_b32_e32 v68, 0
	v_mov_b32_e32 v69, 0
	v_mov_b32_e32 v70, 0
	v_mov_b32_e32 v71, 0
	v_mov_b32_e32 v72, 0
	v_mov_b32_e32 v73, 0
	v_mov_b32_e32 v74, 0
	v_mov_b32_e32 v75, 0
	v_mov_b32_e32 v76, 0
	v_mov_b32_e32 v77, 0
	v_mov_b32_e32 v78, 0
	v_mov_b32_e32 v79, 0
	v_mov_b32_e32 v80, 0
	v_mov_b32_e32 v81, 0
	v_mov_b32_e32 v82, 0
	v_mov_b32_e32 v83, 0
	v_mov_b32_e32 v84, 0
	v_mov_b32_e32 v85, 0
	v_mov_b32_e32 v86, 0
	v_mov_b32_e32 v87, 0
	v_mov_b32_e32 v88, 0
	v_mov_b32_e32 v89, 0
	v_mov_b32_e32 v90, 0
	v_mov_b32_e32 v91, 0
	v_mov_b32_e32 v92, 0
	v_mov_b32_e32 v93, 0
	v_mov_b32_e32 v94, 0
	v_mov_b32_e32 v95, 0
	v_mov_b32_e32 v96, 0
	v_mov_b32_e32 v97, 0
	v_mov_b32_e32 v98, 0
	v_mov_b32_e32 v99, 0
	v_mov_b32_e32 v100, 0
	v_mov_b32_e32 v101, 0
	v_mov_b32_e32 v102, 0
	v_mov_b32_e32 v103, 0
	v_mov_b32_e32 v104, 0
	v_mov_b32_e32 v105, 0
	v_mov_b32_e32 v106, 0
	v_mov_b32_e32 v107, 0
	v_mov_b32_e32 v108, 0
	v_mov_b32_e32 v109, 0
	v_mov_b32_e32 v110, 0
	v_mov_b32_e32 v111, 0
	v_mov_b32_e32 v112, 0
	v_mov_b32_e32 v113, 0
	v_mov_b32_e32 v114, 0
	v_mov_b32_e32 v115, 0
	v_mov_b32_e32 v116, 0
	v_mov_b32_e32 v117, 0
	v_mov_b32_e32 v118, 0
	v_mov_b32_e32 v119, 0
	v_mov_b32_e32 v120, 0
	v_mov_b32_e32 v121, 0
	v_mov_b32_e32 v122, 0
	v_mov_b32_e32 v123, 0
	v_mov_b32_e32 v124, 0
	v_mov_b32_e32 v125, 0
	v_mov_b32_e32 v126, 0
	v_mov_b32_e32 v127, 0
	s_mov_b32 s53, 0
.Lfi_k:
	s_barrier
	s_add_u32 m0, s52, 0x0
	s_add_u32 s4, s44, 0x0
	s_addc_u32 s5, s45, 0
	global_load_lds_dwordx4 v224, s[4:5]
	s_add_u32 m0, s52, 0x1000
	s_add_u32 s4, s44, 0x11000
	s_addc_u32 s5, s45, 0
	global_load_lds_dwordx4 v224, s[4:5]
	s_add_u32 m0, s52, 0x2000
	s_add_u32 s4, s44, 0x22000
	s_addc_u32 s5, s45, 0
	global_load_lds_dwordx4 v224, s[4:5]
	s_add_u32 m0, s52, 0x3000
	s_add_u32 s4, s44, 0x33000
	s_addc_u32 s5, s45, 0
	global_load_lds_dwordx4 v224, s[4:5]
	s_add_u32 m0, s52, 0x4000
	s_add_u32 s4, s44, 0x44000
	s_addc_u32 s5, s45, 0
	global_load_lds_dwordx4 v224, s[4:5]
	s_add_u32 m0, s52, 0x5000
	s_add_u32 s4, s44, 0x55000
	s_addc_u32 s5, s45, 0
	global_load_lds_dwordx4 v224, s[4:5]
	s_add_u32 m0, s52, 0x6000
	s_add_u32 s4, s44, 0x66000
	s_addc_u32 s5, s45, 0
	global_load_lds_dwordx4 v224, s[4:5]
	s_add_u32 m0, s52, 0x7000
	s_add_u32 s4, s44, 0x77000
	s_addc_u32 s5, s45, 0
	global_load_lds_dwordx4 v224, s[4:5]
	s_add_u32 m0, s52, 0x8000
	s_add_u32 s4, s46, 0x0
	s_addc_u32 s5, s47, 0
	global_load_lds_dwordx4 v168, s[4:5]
	s_add_u32 m0, s52, 0x9000
	s_add_u32 s4, s46, 0x11000
	s_addc_u32 s5, s47, 0
	global_load_lds_dwordx4 v168, s[4:5]
	s_add_u32 m0, s52, 0xa000
	s_add_u32 s4, s46, 0x22000
	s_addc_u32 s5, s47, 0
	global_load_lds_dwordx4 v168, s[4:5]
	s_add_u32 m0, s52, 0xb000
	s_add_u32 s4, s46, 0x33000
	s_addc_u32 s5, s47, 0
	global_load_lds_dwordx4 v168, s[4:5]
	s_add_u32 s44, s44, 0x80
	s_addc_u32 s45, s45, 0
	s_add_u32 s46, s46, 0x80
	s_addc_u32 s47, s47, 0
	s_waitcnt vmcnt(0)
	s_barrier
	ds_read_b128 v[204:207], v222
	ds_read_b128 v[208:211], v222 offset:2048
	ds_read_b128 v[212:215], v222 offset:4096
	ds_read_b128 v[216:219], v222 offset:6144
	ds_read_b128 a[0:3], v223
	ds_read_b128 a[4:7], v223 offset:2048
	ds_read_b128 a[8:11], v223 offset:4096
	ds_read_b128 a[12:15], v223 offset:6144
	ds_read_b128 v[136:139], v220
	ds_read_b128 v[140:143], v220 offset:2048
	ds_read_b128 v[144:147], v220 offset:4096
	ds_read_b128 v[148:151], v220 offset:6144
	ds_read_b128 v[152:155], v220 offset:8192
	ds_read_b128 v[156:159], v220 offset:10240
	ds_read_b128 v[160:163], v220 offset:12288
	ds_read_b128 v[164:167], v220 offset:14336
	s_waitcnt lgkmcnt(7)
	v_mfma_f32_16x16x32_bf16 v[0:3], v[136:139], v[204:207], v[0:3]
	v_mfma_f32_16x16x32_bf16 v[4:7], v[136:139], v[208:211], v[4:7]
	v_mfma_f32_16x16x32_bf16 v[8:11], v[136:139], v[212:215], v[8:11]
	v_mfma_f32_16x16x32_bf16 v[12:15], v[136:139], v[216:219], v[12:15]
	ds_read_b128 v[136:139], v221
	s_waitcnt lgkmcnt(7)
	v_mfma_f32_16x16x32_bf16 v[16:19], v[140:143], v[204:207], v[16:19]
	v_mfma_f32_16x16x32_bf16 v[20:23], v[140:143], v[208:211], v[20:23]
	v_mfma_f32_16x16x32_bf16 v[24:27], v[140:143], v[212:215], v[24:27]
	v_mfma_f32_16x16x32_bf16 v[28:31], v[140:143], v[216:219], v[28:31]
	ds_read_b128 v[140:143], v221 offset:2048
	s_waitcnt lgkmcnt(7)
	v_mfma_f32_16x16x32_bf16 v[32:35], v[144:147], v[204:207], v[32:35]
	v_mfma_f32_16x16x32_bf16 v[36:39], v[144:147], v[208:211], v[36:39]
	v_mfma_f32_16x16x32_bf16 v[40:43], v[144:147], v[212:215], v[40:43]
	v_mfma_f32_16x16x32_bf16 v[44:47], v[144:147], v[216:219], v[44:47]
	ds_read_b128 v[144:147], v221 offset:4096
	s_waitcnt lgkmcnt(7)
	v_mfma_f32_16x16x32_bf16 v[48:51], v[148:151], v[204:207], v[48:51]
	v_mfma_f32_16x16x32_bf16 v[52:55], v[148:151], v[208:211], v[52:55]
	v_mfma_f32_16x16x32_bf16 v[56:59], v[148:151], v[212:215], v[56:59]
	v_mfma_f32_16x16x32_bf16 v[60:63], v[148:151], v[216:219], v[60:63]
	ds_read_b128 v[148:151], v221 offset:6144
	s_waitcnt lgkmcnt(7)
	v_mfma_f32_16x16x32_bf16 v[64:67], v[152:155], v[204:207], v[64:67]
	v_mfma_f32_16x16x32_bf16 v[68:71], v[152:155], v[208:211], v[68:71]
	v_mfma_f32_16x16x32_bf16 v[72:75], v[152:155], v[212:215], v[72:75]
	v_mfma_f32_16x16x32_bf16 v[76:79], v[152:155], v[216:219], v[76:79]
	ds_read_b128 v[152:155], v221 offset:8192
	s_waitcnt lgkmcnt(7)
	v_mfma_f32_16x16x32_bf16 v[80:83], v[156:159], v[204:207], v[80:83]
	v_mfma_f32_16x16x32_bf16 v[84:87], v[156:159], v[208:211], v[84:87]
	v_mfma_f32_16x16x32_bf16 v[88:91], v[156:159], v[212:215], v[88:91]
	v_mfma_f32_16x16x32_bf16 v[92:95], v[156:159], v[216:219], v[92:95]
	ds_read_b128 v[156:159], v221 offset:10240
	s_waitcnt lgkmcnt(7)
	v_mfma_f32_16x16x32_bf16 v[96:99], v[160:163], v[204:207], v[96:99]
	v_mfma_f32_16x16x32_bf16 v[100:103], v[160:163], v[208:211], v[100:103]
	v_mfma_f32_16x16x32_bf16 v[104:107], v[160:163], v[212:215], v[104:107]
	v_mfma_f32_16x16x32_bf16 v[108:111], v[160:163], v[216:219], v[108:111]
	ds_read_b128 v[160:163], v221 offset:12288
	s_waitcnt lgkmcnt(7)
	v_mfma_f32_16x16x32_bf16 v[112:115], v[164:167], v[204:207], v[112:115]
	v_mfma_f32_16x16x32_bf16 v[116:119], v[164:167], v[208:211], v[116:119]
	v_mfma_f32_16x16x32_bf16 v[120:123], v[164:167], v[212:215], v[120:123]
	v_mfma_f32_16x16x32_bf16 v[124:127], v[164:167], v[216:219], v[124:127]
	ds_read_b128 v[164:167], v221 offset:14336
	s_waitcnt lgkmcnt(7)
	v_mfma_f32_16x16x32_bf16 v[0:3], v[136:139], a[0:3], v[0:3]
	v_mfma_f32_16x16x32_bf16 v[4:7], v[136:139], a[4:7], v[4:7]
	v_mfma_f32_16x16x32_bf16 v[8:11], v[136:139], a[8:11], v[8:11]
	v_mfma_f32_16x16x32_bf16 v[12:15], v[136:139], a[12:15], v[12:15]
	s_waitcnt lgkmcnt(6)
	v_mfma_f32_16x16x32_bf16 v[16:19], v[140:143], a[0:3], v[16:19]
	v_mfma_f32_16x16x32_bf16 v[20:23], v[140:143], a[4:7], v[20:23]
	v_mfma_f32_16x16x32_bf16 v[24:27], v[140:143], a[8:11], v[24:27]
	v_mfma_f32_16x16x32_bf16 v[28:31], v[140:143], a[12:15], v[28:31]
	s_waitcnt lgkmcnt(5)
	v_mfma_f32_16x16x32_bf16 v[32:35], v[144:147], a[0:3], v[32:35]
	v_mfma_f32_16x16x32_bf16 v[36:39], v[144:147], a[4:7], v[36:39]
	v_mfma_f32_16x16x32_bf16 v[40:43], v[144:147], a[8:11], v[40:43]
	v_mfma_f32_16x16x32_bf16 v[44:47], v[144:147], a[12:15], v[44:47]
	s_waitcnt lgkmcnt(4)
	v_mfma_f32_16x16x32_bf16 v[48:51], v[148:151], a[0:3], v[48:51]
	v_mfma_f32_16x16x32_bf16 v[52:55], v[148:151], a[4:7], v[52:55]
	v_mfma_f32_16x16x32_bf16 v[56:59], v[148:151], a[8:11], v[56:59]
	v_mfma_f32_16x16x32_bf16 v[60:63], v[148:151], a[12:15], v[60:63]
	s_waitcnt lgkmcnt(3)
	v_mfma_f32_16x16x32_bf16 v[64:67], v[152:155], a[0:3], v[64:67]
	v_mfma_f32_16x16x32_bf16 v[68:71], v[152:155], a[4:7], v[68:71]
	v_mfma_f32_16x16x32_bf16 v[72:75], v[152:155], a[8:11], v[72:75]
	v_mfma_f32_16x16x32_bf16 v[76:79], v[152:155], a[12:15], v[76:79]
	s_waitcnt lgkmcnt(2)
	v_mfma_f32_16x16x32_bf16 v[80:83], v[156:159], a[0:3], v[80:83]
	v_mfma_f32_16x16x32_bf16 v[84:87], v[156:159], a[4:7], v[84:87]
	v_mfma_f32_16x16x32_bf16 v[88:91], v[156:159], a[8:11], v[88:91]
	v_mfma_f32_16x16x32_bf16 v[92:95], v[156:159], a[12:15], v[92:95]
	s_waitcnt lgkmcnt(1)
	v_mfma_f32_16x16x32_bf16 v[96:99], v[160:163], a[0:3], v[96:99]
	v_mfma_f32_16x16x32_bf16 v[100:103], v[160:163], a[4:7], v[100:103]
	v_mfma_f32_16x16x32_bf16 v[104:107], v[160:163], a[8:11], v[104:107]
	v_mfma_f32_16x16x32_bf16 v[108:111], v[160:163], a[12:15], v[108:111]
	s_waitcnt lgkmcnt(0)
	v_mfma_f32_16x16x32_bf16 v[112:115], v[164:167], a[0:3], v[112:115]
	v_mfma_f32_16x16x32_bf16 v[116:119], v[164:167], a[4:7], v[116:119]
	v_mfma_f32_16x16x32_bf16 v[120:123], v[164:167], a[8:11], v[120:123]
	v_mfma_f32_16x16x32_bf16 v[124:127], v[164:167], a[12:15], v[124:127]
	s_add_u32 s53, s53, 1
	s_cmp_lt_u32 s53, 16
	s_cbranch_scc1 .Lfi_k
	s_nop 7
	s_nop 7
	v_mov_b32_e32 v226, s50
	v_mov_b32_e32 v227, s51
	v_mov_b32_e32 v229, 0
	v_add_co_u32_e32 v226, vcc, v226, v225
	s_nop 1
	v_addc_co_u32_e32 v227, vcc, 0, v227, vcc
	s_mov_b64 s[56:57], 0x1680
	s_mov_b64 s[40:41], 0x12480
	v_mul_f32_e32 v228, 0xbfb8aa3b, v0
	v_exp_f32_e32 v228, v228
	s_nop 0
	v_add_f32_e32 v229, 1.0, v228
	v_div_scale_f32 v230, s[44:45], v229, v229, v0
	v_rcp_f32_e32 v231, v230
	v_div_scale_f32 v232, vcc, v0, v229, v0
	s_nop 0
	v_fma_f32 v131, -v230, v231, 1.0
	v_fmac_f32_e32 v231, v131, v231
	v_mul_f32_e32 v233, v232, v231
	v_fma_f32 v131, -v230, v233, v232
	v_fmac_f32_e32 v233, v131, v231
	v_fma_f32 v230, -v230, v233, v232
	v_div_fmas_f32 v230, v230, v231, v233
	v_div_fixup_f32 v135, v230, v229, v0
	v_mul_f32_e32 v135, v8, v135
	v_mul_f32_e32 v228, 0xbfb8aa3b, v4
	v_exp_f32_e32 v228, v228
	s_nop 0
	v_add_f32_e32 v229, 1.0, v228
	v_div_scale_f32 v230, s[44:45], v229, v229, v4
	v_rcp_f32_e32 v231, v230
	v_div_scale_f32 v232, vcc, v4, v229, v4
	s_nop 0
	v_fma_f32 v131, -v230, v231, 1.0
	v_fmac_f32_e32 v231, v131, v231
	v_mul_f32_e32 v233, v232, v231
	v_fma_f32 v131, -v230, v233, v232
	v_fmac_f32_e32 v233, v131, v231
	v_fma_f32 v230, -v230, v233, v232
	v_div_fmas_f32 v230, v230, v231, v233
	v_div_fixup_f32 v133, v230, v229, v4
	v_mul_f32_e32 v133, v12, v133
	v_cvt_pk_bf16_f32 v133, v135, v133
	global_store_dword v[226:227], v133, off
	v_lshl_add_u64 v[226:227], v[226:227], 0, s[56:57]
	v_mul_f32_e32 v228, 0xbfb8aa3b, v1
	v_exp_f32_e32 v228, v228
	s_nop 0
	v_add_f32_e32 v229, 1.0, v228
	v_div_scale_f32 v230, s[44:45], v229, v229, v1
	v_rcp_f32_e32 v231, v230
	v_div_scale_f32 v232, vcc, v1, v229, v1
	s_nop 0
	v_fma_f32 v131, -v230, v231, 1.0
	v_fmac_f32_e32 v231, v131, v231
	v_mul_f32_e32 v233, v232, v231
	v_fma_f32 v131, -v230, v233, v232
	v_fmac_f32_e32 v233, v131, v231
	v_fma_f32 v230, -v230, v233, v232
	v_div_fmas_f32 v230, v230, v231, v233
	v_div_fixup_f32 v135, v230, v229, v1
	v_mul_f32_e32 v135, v9, v135
	v_mul_f32_e32 v228, 0xbfb8aa3b, v5
	v_exp_f32_e32 v228, v228
	s_nop 0
	v_add_f32_e32 v229, 1.0, v228
	v_div_scale_f32 v230, s[44:45], v229, v229, v5
	v_rcp_f32_e32 v231, v230
	v_div_scale_f32 v232, vcc, v5, v229, v5
	s_nop 0
	v_fma_f32 v131, -v230, v231, 1.0
	v_fmac_f32_e32 v231, v131, v231
	v_mul_f32_e32 v233, v232, v231
	v_fma_f32 v131, -v230, v233, v232
	v_fmac_f32_e32 v233, v131, v231
	v_fma_f32 v230, -v230, v233, v232
	v_div_fmas_f32 v230, v230, v231, v233
	v_div_fixup_f32 v133, v230, v229, v5
	v_mul_f32_e32 v133, v13, v133
	v_cvt_pk_bf16_f32 v133, v135, v133
	global_store_dword v[226:227], v133, off
	v_lshl_add_u64 v[226:227], v[226:227], 0, s[56:57]
	v_mul_f32_e32 v228, 0xbfb8aa3b, v2
	v_exp_f32_e32 v228, v228
	s_nop 0
	v_add_f32_e32 v229, 1.0, v228
	v_div_scale_f32 v230, s[44:45], v229, v229, v2
	v_rcp_f32_e32 v231, v230
	v_div_scale_f32 v232, vcc, v2, v229, v2
	s_nop 0
	v_fma_f32 v131, -v230, v231, 1.0
	v_fmac_f32_e32 v231, v131, v231
	v_mul_f32_e32 v233, v232, v231
	v_fma_f32 v131, -v230, v233, v232
	v_fmac_f32_e32 v233, v131, v231
	v_fma_f32 v230, -v230, v233, v232
	v_div_fmas_f32 v230, v230, v231, v233
	v_div_fixup_f32 v135, v230, v229, v2
	v_mul_f32_e32 v135, v10, v135
	v_mul_f32_e32 v228, 0xbfb8aa3b, v6
	v_exp_f32_e32 v228, v228
	s_nop 0
	v_add_f32_e32 v229, 1.0, v228
	v_div_scale_f32 v230, s[44:45], v229, v229, v6
	v_rcp_f32_e32 v231, v230
	v_div_scale_f32 v232, vcc, v6, v229, v6
	s_nop 0
	v_fma_f32 v131, -v230, v231, 1.0
	v_fmac_f32_e32 v231, v131, v231
	v_mul_f32_e32 v233, v232, v231
	v_fma_f32 v131, -v230, v233, v232
	v_fmac_f32_e32 v233, v131, v231
	v_fma_f32 v230, -v230, v233, v232
	v_div_fmas_f32 v230, v230, v231, v233
	v_div_fixup_f32 v133, v230, v229, v6
	v_mul_f32_e32 v133, v14, v133
	v_cvt_pk_bf16_f32 v133, v135, v133
	global_store_dword v[226:227], v133, off
	v_lshl_add_u64 v[226:227], v[226:227], 0, s[56:57]
	v_mul_f32_e32 v228, 0xbfb8aa3b, v3
	v_exp_f32_e32 v228, v228
	s_nop 0
	v_add_f32_e32 v229, 1.0, v228
	v_div_scale_f32 v230, s[44:45], v229, v229, v3
	v_rcp_f32_e32 v231, v230
	v_div_scale_f32 v232, vcc, v3, v229, v3
	s_nop 0
	v_fma_f32 v131, -v230, v231, 1.0
	v_fmac_f32_e32 v231, v131, v231
	v_mul_f32_e32 v233, v232, v231
	v_fma_f32 v131, -v230, v233, v232
	v_fmac_f32_e32 v233, v131, v231
	v_fma_f32 v230, -v230, v233, v232
	v_div_fmas_f32 v230, v230, v231, v233
	v_div_fixup_f32 v135, v230, v229, v3
	v_mul_f32_e32 v135, v11, v135
	v_mul_f32_e32 v228, 0xbfb8aa3b, v7
	v_exp_f32_e32 v228, v228
	s_nop 0
	v_add_f32_e32 v229, 1.0, v228
	v_div_scale_f32 v230, s[44:45], v229, v229, v7
	v_rcp_f32_e32 v231, v230
	v_div_scale_f32 v232, vcc, v7, v229, v7
	s_nop 0
	v_fma_f32 v131, -v230, v231, 1.0
	v_fmac_f32_e32 v231, v131, v231
	v_mul_f32_e32 v233, v232, v231
	v_fma_f32 v131, -v230, v233, v232
	v_fmac_f32_e32 v233, v131, v231
	v_fma_f32 v230, -v230, v233, v232
	v_div_fmas_f32 v230, v230, v231, v233
	v_div_fixup_f32 v133, v230, v229, v7
	v_mul_f32_e32 v133, v15, v133
	v_cvt_pk_bf16_f32 v133, v135, v133
	global_store_dword v[226:227], v133, off
	v_lshl_add_u64 v[226:227], v[226:227], 0, s[40:41]
	v_mul_f32_e32 v228, 0xbfb8aa3b, v16
	v_exp_f32_e32 v228, v228
	s_nop 0
	v_add_f32_e32 v229, 1.0, v228
	v_div_scale_f32 v230, s[44:45], v229, v229, v16
	v_rcp_f32_e32 v231, v230
	v_div_scale_f32 v232, vcc, v16, v229, v16
	s_nop 0
	v_fma_f32 v131, -v230, v231, 1.0
	v_fmac_f32_e32 v231, v131, v231
	v_mul_f32_e32 v233, v232, v231
	v_fma_f32 v131, -v230, v233, v232
	v_fmac_f32_e32 v233, v131, v231
	v_fma_f32 v230, -v230, v233, v232
	v_div_fmas_f32 v230, v230, v231, v233
	v_div_fixup_f32 v135, v230, v229, v16
	v_mul_f32_e32 v135, v24, v135
	v_mul_f32_e32 v228, 0xbfb8aa3b, v20
	v_exp_f32_e32 v228, v228
	s_nop 0
	v_add_f32_e32 v229, 1.0, v228
	v_div_scale_f32 v230, s[44:45], v229, v229, v20
	v_rcp_f32_e32 v231, v230
	v_div_scale_f32 v232, vcc, v20, v229, v20
	s_nop 0
	v_fma_f32 v131, -v230, v231, 1.0
	v_fmac_f32_e32 v231, v131, v231
	v_mul_f32_e32 v233, v232, v231
	v_fma_f32 v131, -v230, v233, v232
	v_fmac_f32_e32 v233, v131, v231
	v_fma_f32 v230, -v230, v233, v232
	v_div_fmas_f32 v230, v230, v231, v233
	v_div_fixup_f32 v133, v230, v229, v20
	v_mul_f32_e32 v133, v28, v133
	v_cvt_pk_bf16_f32 v133, v135, v133
	global_store_dword v[226:227], v133, off
	v_lshl_add_u64 v[226:227], v[226:227], 0, s[56:57]
	v_mul_f32_e32 v228, 0xbfb8aa3b, v17
	v_exp_f32_e32 v228, v228
	s_nop 0
	v_add_f32_e32 v229, 1.0, v228
	v_div_scale_f32 v230, s[44:45], v229, v229, v17
	v_rcp_f32_e32 v231, v230
	v_div_scale_f32 v232, vcc, v17, v229, v17
	s_nop 0
	v_fma_f32 v131, -v230, v231, 1.0
	v_fmac_f32_e32 v231, v131, v231
	v_mul_f32_e32 v233, v232, v231
	v_fma_f32 v131, -v230, v233, v232
	v_fmac_f32_e32 v233, v131, v231
	v_fma_f32 v230, -v230, v233, v232
	v_div_fmas_f32 v230, v230, v231, v233
	v_div_fixup_f32 v135, v230, v229, v17
	v_mul_f32_e32 v135, v25, v135
	v_mul_f32_e32 v228, 0xbfb8aa3b, v21
	v_exp_f32_e32 v228, v228
	s_nop 0
	v_add_f32_e32 v229, 1.0, v228
	v_div_scale_f32 v230, s[44:45], v229, v229, v21
	v_rcp_f32_e32 v231, v230
	v_div_scale_f32 v232, vcc, v21, v229, v21
	s_nop 0
	v_fma_f32 v131, -v230, v231, 1.0
	v_fmac_f32_e32 v231, v131, v231
	v_mul_f32_e32 v233, v232, v231
	v_fma_f32 v131, -v230, v233, v232
	v_fmac_f32_e32 v233, v131, v231
	v_fma_f32 v230, -v230, v233, v232
	v_div_fmas_f32 v230, v230, v231, v233
	v_div_fixup_f32 v133, v230, v229, v21
	v_mul_f32_e32 v133, v29, v133
	v_cvt_pk_bf16_f32 v133, v135, v133
	global_store_dword v[226:227], v133, off
	v_lshl_add_u64 v[226:227], v[226:227], 0, s[56:57]
	v_mul_f32_e32 v228, 0xbfb8aa3b, v18
	v_exp_f32_e32 v228, v228
	s_nop 0
	v_add_f32_e32 v229, 1.0, v228
	v_div_scale_f32 v230, s[44:45], v229, v229, v18
	v_rcp_f32_e32 v231, v230
	v_div_scale_f32 v232, vcc, v18, v229, v18
	s_nop 0
	v_fma_f32 v131, -v230, v231, 1.0
	v_fmac_f32_e32 v231, v131, v231
	v_mul_f32_e32 v233, v232, v231
	v_fma_f32 v131, -v230, v233, v232
	v_fmac_f32_e32 v233, v131, v231
	v_fma_f32 v230, -v230, v233, v232
	v_div_fmas_f32 v230, v230, v231, v233
	v_div_fixup_f32 v135, v230, v229, v18
	v_mul_f32_e32 v135, v26, v135
	v_mul_f32_e32 v228, 0xbfb8aa3b, v22
	v_exp_f32_e32 v228, v228
	s_nop 0
	v_add_f32_e32 v229, 1.0, v228
	v_div_scale_f32 v230, s[44:45], v229, v229, v22
	v_rcp_f32_e32 v231, v230
	v_div_scale_f32 v232, vcc, v22, v229, v22
	s_nop 0
	v_fma_f32 v131, -v230, v231, 1.0
	v_fmac_f32_e32 v231, v131, v231
	v_mul_f32_e32 v233, v232, v231
	v_fma_f32 v131, -v230, v233, v232
	v_fmac_f32_e32 v233, v131, v231
	v_fma_f32 v230, -v230, v233, v232
	v_div_fmas_f32 v230, v230, v231, v233
	v_div_fixup_f32 v133, v230, v229, v22
	v_mul_f32_e32 v133, v30, v133
	v_cvt_pk_bf16_f32 v133, v135, v133
	global_store_dword v[226:227], v133, off
	v_lshl_add_u64 v[226:227], v[226:227], 0, s[56:57]
	v_mul_f32_e32 v228, 0xbfb8aa3b, v19
	v_exp_f32_e32 v228, v228
	s_nop 0
	v_add_f32_e32 v229, 1.0, v228
	v_div_scale_f32 v230, s[44:45], v229, v229, v19
	v_rcp_f32_e32 v231, v230
	v_div_scale_f32 v232, vcc, v19, v229, v19
	s_nop 0
	v_fma_f32 v131, -v230, v231, 1.0
	v_fmac_f32_e32 v231, v131, v231
	v_mul_f32_e32 v233, v232, v231
	v_fma_f32 v131, -v230, v233, v232
	v_fmac_f32_e32 v233, v131, v231
	v_fma_f32 v230, -v230, v233, v232
	v_div_fmas_f32 v230, v230, v231, v233
	v_div_fixup_f32 v135, v230, v229, v19
	v_mul_f32_e32 v135, v27, v135
	v_mul_f32_e32 v228, 0xbfb8aa3b, v23
	v_exp_f32_e32 v228, v228
	s_nop 0
	v_add_f32_e32 v229, 1.0, v228
	v_div_scale_f32 v230, s[44:45], v229, v229, v23
	v_rcp_f32_e32 v231, v230
	v_div_scale_f32 v232, vcc, v23, v229, v23
	s_nop 0
	v_fma_f32 v131, -v230, v231, 1.0
	v_fmac_f32_e32 v231, v131, v231
	v_mul_f32_e32 v233, v232, v231
	v_fma_f32 v131, -v230, v233, v232
	v_fmac_f32_e32 v233, v131, v231
	v_fma_f32 v230, -v230, v233, v232
	v_div_fmas_f32 v230, v230, v231, v233
	v_div_fixup_f32 v133, v230, v229, v23
	v_mul_f32_e32 v133, v31, v133
	v_cvt_pk_bf16_f32 v133, v135, v133
	global_store_dword v[226:227], v133, off
	v_lshl_add_u64 v[226:227], v[226:227], 0, s[40:41]
	v_mul_f32_e32 v228, 0xbfb8aa3b, v32
	v_exp_f32_e32 v228, v228
	s_nop 0
	v_add_f32_e32 v229, 1.0, v228
	v_div_scale_f32 v230, s[44:45], v229, v229, v32
	v_rcp_f32_e32 v231, v230
	v_div_scale_f32 v232, vcc, v32, v229, v32
	s_nop 0
	v_fma_f32 v131, -v230, v231, 1.0
	v_fmac_f32_e32 v231, v131, v231
	v_mul_f32_e32 v233, v232, v231
	v_fma_f32 v131, -v230, v233, v232
	v_fmac_f32_e32 v233, v131, v231
	v_fma_f32 v230, -v230, v233, v232
	v_div_fmas_f32 v230, v230, v231, v233
	v_div_fixup_f32 v135, v230, v229, v32
	v_mul_f32_e32 v135, v40, v135
	v_mul_f32_e32 v228, 0xbfb8aa3b, v36
	v_exp_f32_e32 v228, v228
	s_nop 0
	v_add_f32_e32 v229, 1.0, v228
	v_div_scale_f32 v230, s[44:45], v229, v229, v36
	v_rcp_f32_e32 v231, v230
	v_div_scale_f32 v232, vcc, v36, v229, v36
	s_nop 0
	v_fma_f32 v131, -v230, v231, 1.0
	v_fmac_f32_e32 v231, v131, v231
	v_mul_f32_e32 v233, v232, v231
	v_fma_f32 v131, -v230, v233, v232
	v_fmac_f32_e32 v233, v131, v231
	v_fma_f32 v230, -v230, v233, v232
	v_div_fmas_f32 v230, v230, v231, v233
	v_div_fixup_f32 v133, v230, v229, v36
	v_mul_f32_e32 v133, v44, v133
	v_cvt_pk_bf16_f32 v133, v135, v133
	global_store_dword v[226:227], v133, off
	v_lshl_add_u64 v[226:227], v[226:227], 0, s[56:57]
	v_mul_f32_e32 v228, 0xbfb8aa3b, v33
	v_exp_f32_e32 v228, v228
	s_nop 0
	v_add_f32_e32 v229, 1.0, v228
	v_div_scale_f32 v230, s[44:45], v229, v229, v33
	v_rcp_f32_e32 v231, v230
	v_div_scale_f32 v232, vcc, v33, v229, v33
	s_nop 0
	v_fma_f32 v131, -v230, v231, 1.0
	v_fmac_f32_e32 v231, v131, v231
	v_mul_f32_e32 v233, v232, v231
	v_fma_f32 v131, -v230, v233, v232
	v_fmac_f32_e32 v233, v131, v231
	v_fma_f32 v230, -v230, v233, v232
	v_div_fmas_f32 v230, v230, v231, v233
	v_div_fixup_f32 v135, v230, v229, v33
	v_mul_f32_e32 v135, v41, v135
	v_mul_f32_e32 v228, 0xbfb8aa3b, v37
	v_exp_f32_e32 v228, v228
	s_nop 0
	v_add_f32_e32 v229, 1.0, v228
	v_div_scale_f32 v230, s[44:45], v229, v229, v37
	v_rcp_f32_e32 v231, v230
	v_div_scale_f32 v232, vcc, v37, v229, v37
	s_nop 0
	v_fma_f32 v131, -v230, v231, 1.0
	v_fmac_f32_e32 v231, v131, v231
	v_mul_f32_e32 v233, v232, v231
	v_fma_f32 v131, -v230, v233, v232
	v_fmac_f32_e32 v233, v131, v231
	v_fma_f32 v230, -v230, v233, v232
	v_div_fmas_f32 v230, v230, v231, v233
	v_div_fixup_f32 v133, v230, v229, v37
	v_mul_f32_e32 v133, v45, v133
	v_cvt_pk_bf16_f32 v133, v135, v133
	global_store_dword v[226:227], v133, off
	v_lshl_add_u64 v[226:227], v[226:227], 0, s[56:57]
	v_mul_f32_e32 v228, 0xbfb8aa3b, v34
	v_exp_f32_e32 v228, v228
	s_nop 0
	v_add_f32_e32 v229, 1.0, v228
	v_div_scale_f32 v230, s[44:45], v229, v229, v34
	v_rcp_f32_e32 v231, v230
	v_div_scale_f32 v232, vcc, v34, v229, v34
	s_nop 0
	v_fma_f32 v131, -v230, v231, 1.0
	v_fmac_f32_e32 v231, v131, v231
	v_mul_f32_e32 v233, v232, v231
	v_fma_f32 v131, -v230, v233, v232
	v_fmac_f32_e32 v233, v131, v231
	v_fma_f32 v230, -v230, v233, v232
	v_div_fmas_f32 v230, v230, v231, v233
	v_div_fixup_f32 v135, v230, v229, v34
	v_mul_f32_e32 v135, v42, v135
	v_mul_f32_e32 v228, 0xbfb8aa3b, v38
	v_exp_f32_e32 v228, v228
	s_nop 0
	v_add_f32_e32 v229, 1.0, v228
	v_div_scale_f32 v230, s[44:45], v229, v229, v38
	v_rcp_f32_e32 v231, v230
	v_div_scale_f32 v232, vcc, v38, v229, v38
	s_nop 0
	v_fma_f32 v131, -v230, v231, 1.0
	v_fmac_f32_e32 v231, v131, v231
	v_mul_f32_e32 v233, v232, v231
	v_fma_f32 v131, -v230, v233, v232
	v_fmac_f32_e32 v233, v131, v231
	v_fma_f32 v230, -v230, v233, v232
	v_div_fmas_f32 v230, v230, v231, v233
	v_div_fixup_f32 v133, v230, v229, v38
	v_mul_f32_e32 v133, v46, v133
	v_cvt_pk_bf16_f32 v133, v135, v133
	global_store_dword v[226:227], v133, off
	v_lshl_add_u64 v[226:227], v[226:227], 0, s[56:57]
	v_mul_f32_e32 v228, 0xbfb8aa3b, v35
	v_exp_f32_e32 v228, v228
	s_nop 0
	v_add_f32_e32 v229, 1.0, v228
	v_div_scale_f32 v230, s[44:45], v229, v229, v35
	v_rcp_f32_e32 v231, v230
	v_div_scale_f32 v232, vcc, v35, v229, v35
	s_nop 0
	v_fma_f32 v131, -v230, v231, 1.0
	v_fmac_f32_e32 v231, v131, v231
	v_mul_f32_e32 v233, v232, v231
	v_fma_f32 v131, -v230, v233, v232
	v_fmac_f32_e32 v233, v131, v231
	v_fma_f32 v230, -v230, v233, v232
	v_div_fmas_f32 v230, v230, v231, v233
	v_div_fixup_f32 v135, v230, v229, v35
	v_mul_f32_e32 v135, v43, v135
	v_mul_f32_e32 v228, 0xbfb8aa3b, v39
	v_exp_f32_e32 v228, v228
	s_nop 0
	v_add_f32_e32 v229, 1.0, v228
	v_div_scale_f32 v230, s[44:45], v229, v229, v39
	v_rcp_f32_e32 v231, v230
	v_div_scale_f32 v232, vcc, v39, v229, v39
	s_nop 0
	v_fma_f32 v131, -v230, v231, 1.0
	v_fmac_f32_e32 v231, v131, v231
	v_mul_f32_e32 v233, v232, v231
	v_fma_f32 v131, -v230, v233, v232
	v_fmac_f32_e32 v233, v131, v231
	v_fma_f32 v230, -v230, v233, v232
	v_div_fmas_f32 v230, v230, v231, v233
	v_div_fixup_f32 v133, v230, v229, v39
	v_mul_f32_e32 v133, v47, v133
	v_cvt_pk_bf16_f32 v133, v135, v133
	global_store_dword v[226:227], v133, off
	v_lshl_add_u64 v[226:227], v[226:227], 0, s[40:41]
	v_mul_f32_e32 v228, 0xbfb8aa3b, v48
	v_exp_f32_e32 v228, v228
	s_nop 0
	v_add_f32_e32 v229, 1.0, v228
	v_div_scale_f32 v230, s[44:45], v229, v229, v48
	v_rcp_f32_e32 v231, v230
	v_div_scale_f32 v232, vcc, v48, v229, v48
	s_nop 0
	v_fma_f32 v131, -v230, v231, 1.0
	v_fmac_f32_e32 v231, v131, v231
	v_mul_f32_e32 v233, v232, v231
	v_fma_f32 v131, -v230, v233, v232
	v_fmac_f32_e32 v233, v131, v231
	v_fma_f32 v230, -v230, v233, v232
	v_div_fmas_f32 v230, v230, v231, v233
	v_div_fixup_f32 v135, v230, v229, v48
	v_mul_f32_e32 v135, v56, v135
	v_mul_f32_e32 v228, 0xbfb8aa3b, v52
	v_exp_f32_e32 v228, v228
	s_nop 0
	v_add_f32_e32 v229, 1.0, v228
	v_div_scale_f32 v230, s[44:45], v229, v229, v52
	v_rcp_f32_e32 v231, v230
	v_div_scale_f32 v232, vcc, v52, v229, v52
	s_nop 0
	v_fma_f32 v131, -v230, v231, 1.0
	v_fmac_f32_e32 v231, v131, v231
	v_mul_f32_e32 v233, v232, v231
	v_fma_f32 v131, -v230, v233, v232
	v_fmac_f32_e32 v233, v131, v231
	v_fma_f32 v230, -v230, v233, v232
	v_div_fmas_f32 v230, v230, v231, v233
	v_div_fixup_f32 v133, v230, v229, v52
	v_mul_f32_e32 v133, v60, v133
	v_cvt_pk_bf16_f32 v133, v135, v133
	global_store_dword v[226:227], v133, off
	v_lshl_add_u64 v[226:227], v[226:227], 0, s[56:57]
	v_mul_f32_e32 v228, 0xbfb8aa3b, v49
	v_exp_f32_e32 v228, v228
	s_nop 0
	v_add_f32_e32 v229, 1.0, v228
	v_div_scale_f32 v230, s[44:45], v229, v229, v49
	v_rcp_f32_e32 v231, v230
	v_div_scale_f32 v232, vcc, v49, v229, v49
	s_nop 0
	v_fma_f32 v131, -v230, v231, 1.0
	v_fmac_f32_e32 v231, v131, v231
	v_mul_f32_e32 v233, v232, v231
	v_fma_f32 v131, -v230, v233, v232
	v_fmac_f32_e32 v233, v131, v231
	v_fma_f32 v230, -v230, v233, v232
	v_div_fmas_f32 v230, v230, v231, v233
	v_div_fixup_f32 v135, v230, v229, v49
	v_mul_f32_e32 v135, v57, v135
	v_mul_f32_e32 v228, 0xbfb8aa3b, v53
	v_exp_f32_e32 v228, v228
	s_nop 0
	v_add_f32_e32 v229, 1.0, v228
	v_div_scale_f32 v230, s[44:45], v229, v229, v53
	v_rcp_f32_e32 v231, v230
	v_div_scale_f32 v232, vcc, v53, v229, v53
	s_nop 0
	v_fma_f32 v131, -v230, v231, 1.0
	v_fmac_f32_e32 v231, v131, v231
	v_mul_f32_e32 v233, v232, v231
	v_fma_f32 v131, -v230, v233, v232
	v_fmac_f32_e32 v233, v131, v231
	v_fma_f32 v230, -v230, v233, v232
	v_div_fmas_f32 v230, v230, v231, v233
	v_div_fixup_f32 v133, v230, v229, v53
	v_mul_f32_e32 v133, v61, v133
	v_cvt_pk_bf16_f32 v133, v135, v133
	global_store_dword v[226:227], v133, off
	v_lshl_add_u64 v[226:227], v[226:227], 0, s[56:57]
	v_mul_f32_e32 v228, 0xbfb8aa3b, v50
	v_exp_f32_e32 v228, v228
	s_nop 0
	v_add_f32_e32 v229, 1.0, v228
	v_div_scale_f32 v230, s[44:45], v229, v229, v50
	v_rcp_f32_e32 v231, v230
	v_div_scale_f32 v232, vcc, v50, v229, v50
	s_nop 0
	v_fma_f32 v131, -v230, v231, 1.0
	v_fmac_f32_e32 v231, v131, v231
	v_mul_f32_e32 v233, v232, v231
	v_fma_f32 v131, -v230, v233, v232
	v_fmac_f32_e32 v233, v131, v231
	v_fma_f32 v230, -v230, v233, v232
	v_div_fmas_f32 v230, v230, v231, v233
	v_div_fixup_f32 v135, v230, v229, v50
	v_mul_f32_e32 v135, v58, v135
	v_mul_f32_e32 v228, 0xbfb8aa3b, v54
	v_exp_f32_e32 v228, v228
	s_nop 0
	v_add_f32_e32 v229, 1.0, v228
	v_div_scale_f32 v230, s[44:45], v229, v229, v54
	v_rcp_f32_e32 v231, v230
	v_div_scale_f32 v232, vcc, v54, v229, v54
	s_nop 0
	v_fma_f32 v131, -v230, v231, 1.0
	v_fmac_f32_e32 v231, v131, v231
	v_mul_f32_e32 v233, v232, v231
	v_fma_f32 v131, -v230, v233, v232
	v_fmac_f32_e32 v233, v131, v231
	v_fma_f32 v230, -v230, v233, v232
	v_div_fmas_f32 v230, v230, v231, v233
	v_div_fixup_f32 v133, v230, v229, v54
	v_mul_f32_e32 v133, v62, v133
	v_cvt_pk_bf16_f32 v133, v135, v133
	global_store_dword v[226:227], v133, off
	v_lshl_add_u64 v[226:227], v[226:227], 0, s[56:57]
	v_mul_f32_e32 v228, 0xbfb8aa3b, v51
	v_exp_f32_e32 v228, v228
	s_nop 0
	v_add_f32_e32 v229, 1.0, v228
	v_div_scale_f32 v230, s[44:45], v229, v229, v51
	v_rcp_f32_e32 v231, v230
	v_div_scale_f32 v232, vcc, v51, v229, v51
	s_nop 0
	v_fma_f32 v131, -v230, v231, 1.0
	v_fmac_f32_e32 v231, v131, v231
	v_mul_f32_e32 v233, v232, v231
	v_fma_f32 v131, -v230, v233, v232
	v_fmac_f32_e32 v233, v131, v231
	v_fma_f32 v230, -v230, v233, v232
	v_div_fmas_f32 v230, v230, v231, v233
	v_div_fixup_f32 v135, v230, v229, v51
	v_mul_f32_e32 v135, v59, v135
	v_mul_f32_e32 v228, 0xbfb8aa3b, v55
	v_exp_f32_e32 v228, v228
	s_nop 0
	v_add_f32_e32 v229, 1.0, v228
	v_div_scale_f32 v230, s[44:45], v229, v229, v55
	v_rcp_f32_e32 v231, v230
	v_div_scale_f32 v232, vcc, v55, v229, v55
	s_nop 0
	v_fma_f32 v131, -v230, v231, 1.0
	v_fmac_f32_e32 v231, v131, v231
	v_mul_f32_e32 v233, v232, v231
	v_fma_f32 v131, -v230, v233, v232
	v_fmac_f32_e32 v233, v131, v231
	v_fma_f32 v230, -v230, v233, v232
	v_div_fmas_f32 v230, v230, v231, v233
	v_div_fixup_f32 v133, v230, v229, v55
	v_mul_f32_e32 v133, v63, v133
	v_cvt_pk_bf16_f32 v133, v135, v133
	global_store_dword v[226:227], v133, off
	v_lshl_add_u64 v[226:227], v[226:227], 0, s[40:41]
	v_mul_f32_e32 v228, 0xbfb8aa3b, v64
	v_exp_f32_e32 v228, v228
	s_nop 0
	v_add_f32_e32 v229, 1.0, v228
	v_div_scale_f32 v230, s[44:45], v229, v229, v64
	v_rcp_f32_e32 v231, v230
	v_div_scale_f32 v232, vcc, v64, v229, v64
	s_nop 0
	v_fma_f32 v131, -v230, v231, 1.0
	v_fmac_f32_e32 v231, v131, v231
	v_mul_f32_e32 v233, v232, v231
	v_fma_f32 v131, -v230, v233, v232
	v_fmac_f32_e32 v233, v131, v231
	v_fma_f32 v230, -v230, v233, v232
	v_div_fmas_f32 v230, v230, v231, v233
	v_div_fixup_f32 v135, v230, v229, v64
	v_mul_f32_e32 v135, v72, v135
	v_mul_f32_e32 v228, 0xbfb8aa3b, v68
	v_exp_f32_e32 v228, v228
	s_nop 0
	v_add_f32_e32 v229, 1.0, v228
	v_div_scale_f32 v230, s[44:45], v229, v229, v68
	v_rcp_f32_e32 v231, v230
	v_div_scale_f32 v232, vcc, v68, v229, v68
	s_nop 0
	v_fma_f32 v131, -v230, v231, 1.0
	v_fmac_f32_e32 v231, v131, v231
	v_mul_f32_e32 v233, v232, v231
	v_fma_f32 v131, -v230, v233, v232
	v_fmac_f32_e32 v233, v131, v231
	v_fma_f32 v230, -v230, v233, v232
	v_div_fmas_f32 v230, v230, v231, v233
	v_div_fixup_f32 v133, v230, v229, v68
	v_mul_f32_e32 v133, v76, v133
	v_cvt_pk_bf16_f32 v133, v135, v133
	global_store_dword v[226:227], v133, off
	v_lshl_add_u64 v[226:227], v[226:227], 0, s[56:57]
	v_mul_f32_e32 v228, 0xbfb8aa3b, v65
	v_exp_f32_e32 v228, v228
	s_nop 0
	v_add_f32_e32 v229, 1.0, v228
	v_div_scale_f32 v230, s[44:45], v229, v229, v65
	v_rcp_f32_e32 v231, v230
	v_div_scale_f32 v232, vcc, v65, v229, v65
	s_nop 0
	v_fma_f32 v131, -v230, v231, 1.0
	v_fmac_f32_e32 v231, v131, v231
	v_mul_f32_e32 v233, v232, v231
	v_fma_f32 v131, -v230, v233, v232
	v_fmac_f32_e32 v233, v131, v231
	v_fma_f32 v230, -v230, v233, v232
	v_div_fmas_f32 v230, v230, v231, v233
	v_div_fixup_f32 v135, v230, v229, v65
	v_mul_f32_e32 v135, v73, v135
	v_mul_f32_e32 v228, 0xbfb8aa3b, v69
	v_exp_f32_e32 v228, v228
	s_nop 0
	v_add_f32_e32 v229, 1.0, v228
	v_div_scale_f32 v230, s[44:45], v229, v229, v69
	v_rcp_f32_e32 v231, v230
	v_div_scale_f32 v232, vcc, v69, v229, v69
	s_nop 0
	v_fma_f32 v131, -v230, v231, 1.0
	v_fmac_f32_e32 v231, v131, v231
	v_mul_f32_e32 v233, v232, v231
	v_fma_f32 v131, -v230, v233, v232
	v_fmac_f32_e32 v233, v131, v231
	v_fma_f32 v230, -v230, v233, v232
	v_div_fmas_f32 v230, v230, v231, v233
	v_div_fixup_f32 v133, v230, v229, v69
	v_mul_f32_e32 v133, v77, v133
	v_cvt_pk_bf16_f32 v133, v135, v133
	global_store_dword v[226:227], v133, off
	v_lshl_add_u64 v[226:227], v[226:227], 0, s[56:57]
	v_mul_f32_e32 v228, 0xbfb8aa3b, v66
	v_exp_f32_e32 v228, v228
	s_nop 0
	v_add_f32_e32 v229, 1.0, v228
	v_div_scale_f32 v230, s[44:45], v229, v229, v66
	v_rcp_f32_e32 v231, v230
	v_div_scale_f32 v232, vcc, v66, v229, v66
	s_nop 0
	v_fma_f32 v131, -v230, v231, 1.0
	v_fmac_f32_e32 v231, v131, v231
	v_mul_f32_e32 v233, v232, v231
	v_fma_f32 v131, -v230, v233, v232
	v_fmac_f32_e32 v233, v131, v231
	v_fma_f32 v230, -v230, v233, v232
	v_div_fmas_f32 v230, v230, v231, v233
	v_div_fixup_f32 v135, v230, v229, v66
	v_mul_f32_e32 v135, v74, v135
	v_mul_f32_e32 v228, 0xbfb8aa3b, v70
	v_exp_f32_e32 v228, v228
	s_nop 0
	v_add_f32_e32 v229, 1.0, v228
	v_div_scale_f32 v230, s[44:45], v229, v229, v70
	v_rcp_f32_e32 v231, v230
	v_div_scale_f32 v232, vcc, v70, v229, v70
	s_nop 0
	v_fma_f32 v131, -v230, v231, 1.0
	v_fmac_f32_e32 v231, v131, v231
	v_mul_f32_e32 v233, v232, v231
	v_fma_f32 v131, -v230, v233, v232
	v_fmac_f32_e32 v233, v131, v231
	v_fma_f32 v230, -v230, v233, v232
	v_div_fmas_f32 v230, v230, v231, v233
	v_div_fixup_f32 v133, v230, v229, v70
	v_mul_f32_e32 v133, v78, v133
	v_cvt_pk_bf16_f32 v133, v135, v133
	global_store_dword v[226:227], v133, off
	v_lshl_add_u64 v[226:227], v[226:227], 0, s[56:57]
	v_mul_f32_e32 v228, 0xbfb8aa3b, v67
	v_exp_f32_e32 v228, v228
	s_nop 0
	v_add_f32_e32 v229, 1.0, v228
	v_div_scale_f32 v230, s[44:45], v229, v229, v67
	v_rcp_f32_e32 v231, v230
	v_div_scale_f32 v232, vcc, v67, v229, v67
	s_nop 0
	v_fma_f32 v131, -v230, v231, 1.0
	v_fmac_f32_e32 v231, v131, v231
	v_mul_f32_e32 v233, v232, v231
	v_fma_f32 v131, -v230, v233, v232
	v_fmac_f32_e32 v233, v131, v231
	v_fma_f32 v230, -v230, v233, v232
	v_div_fmas_f32 v230, v230, v231, v233
	v_div_fixup_f32 v135, v230, v229, v67
	v_mul_f32_e32 v135, v75, v135
	v_mul_f32_e32 v228, 0xbfb8aa3b, v71
	v_exp_f32_e32 v228, v228
	s_nop 0
	v_add_f32_e32 v229, 1.0, v228
	v_div_scale_f32 v230, s[44:45], v229, v229, v71
	v_rcp_f32_e32 v231, v230
	v_div_scale_f32 v232, vcc, v71, v229, v71
	s_nop 0
	v_fma_f32 v131, -v230, v231, 1.0
	v_fmac_f32_e32 v231, v131, v231
	v_mul_f32_e32 v233, v232, v231
	v_fma_f32 v131, -v230, v233, v232
	v_fmac_f32_e32 v233, v131, v231
	v_fma_f32 v230, -v230, v233, v232
	v_div_fmas_f32 v230, v230, v231, v233
	v_div_fixup_f32 v133, v230, v229, v71
	v_mul_f32_e32 v133, v79, v133
	v_cvt_pk_bf16_f32 v133, v135, v133
	global_store_dword v[226:227], v133, off
	v_lshl_add_u64 v[226:227], v[226:227], 0, s[40:41]
	v_mul_f32_e32 v228, 0xbfb8aa3b, v80
	v_exp_f32_e32 v228, v228
	s_nop 0
	v_add_f32_e32 v229, 1.0, v228
	v_div_scale_f32 v230, s[44:45], v229, v229, v80
	v_rcp_f32_e32 v231, v230
	v_div_scale_f32 v232, vcc, v80, v229, v80
	s_nop 0
	v_fma_f32 v131, -v230, v231, 1.0
	v_fmac_f32_e32 v231, v131, v231
	v_mul_f32_e32 v233, v232, v231
	v_fma_f32 v131, -v230, v233, v232
	v_fmac_f32_e32 v233, v131, v231
	v_fma_f32 v230, -v230, v233, v232
	v_div_fmas_f32 v230, v230, v231, v233
	v_div_fixup_f32 v135, v230, v229, v80
	v_mul_f32_e32 v135, v88, v135
	v_mul_f32_e32 v228, 0xbfb8aa3b, v84
	v_exp_f32_e32 v228, v228
	s_nop 0
	v_add_f32_e32 v229, 1.0, v228
	v_div_scale_f32 v230, s[44:45], v229, v229, v84
	v_rcp_f32_e32 v231, v230
	v_div_scale_f32 v232, vcc, v84, v229, v84
	s_nop 0
	v_fma_f32 v131, -v230, v231, 1.0
	v_fmac_f32_e32 v231, v131, v231
	v_mul_f32_e32 v233, v232, v231
	v_fma_f32 v131, -v230, v233, v232
	v_fmac_f32_e32 v233, v131, v231
	v_fma_f32 v230, -v230, v233, v232
	v_div_fmas_f32 v230, v230, v231, v233
	v_div_fixup_f32 v133, v230, v229, v84
	v_mul_f32_e32 v133, v92, v133
	v_cvt_pk_bf16_f32 v133, v135, v133
	global_store_dword v[226:227], v133, off
	v_lshl_add_u64 v[226:227], v[226:227], 0, s[56:57]
	v_mul_f32_e32 v228, 0xbfb8aa3b, v81
	v_exp_f32_e32 v228, v228
	s_nop 0
	v_add_f32_e32 v229, 1.0, v228
	v_div_scale_f32 v230, s[44:45], v229, v229, v81
	v_rcp_f32_e32 v231, v230
	v_div_scale_f32 v232, vcc, v81, v229, v81
	s_nop 0
	v_fma_f32 v131, -v230, v231, 1.0
	v_fmac_f32_e32 v231, v131, v231
	v_mul_f32_e32 v233, v232, v231
	v_fma_f32 v131, -v230, v233, v232
	v_fmac_f32_e32 v233, v131, v231
	v_fma_f32 v230, -v230, v233, v232
	v_div_fmas_f32 v230, v230, v231, v233
	v_div_fixup_f32 v135, v230, v229, v81
	v_mul_f32_e32 v135, v89, v135
	v_mul_f32_e32 v228, 0xbfb8aa3b, v85
	v_exp_f32_e32 v228, v228
	s_nop 0
	v_add_f32_e32 v229, 1.0, v228
	v_div_scale_f32 v230, s[44:45], v229, v229, v85
	v_rcp_f32_e32 v231, v230
	v_div_scale_f32 v232, vcc, v85, v229, v85
	s_nop 0
	v_fma_f32 v131, -v230, v231, 1.0
	v_fmac_f32_e32 v231, v131, v231
	v_mul_f32_e32 v233, v232, v231
	v_fma_f32 v131, -v230, v233, v232
	v_fmac_f32_e32 v233, v131, v231
	v_fma_f32 v230, -v230, v233, v232
	v_div_fmas_f32 v230, v230, v231, v233
	v_div_fixup_f32 v133, v230, v229, v85
	v_mul_f32_e32 v133, v93, v133
	v_cvt_pk_bf16_f32 v133, v135, v133
	global_store_dword v[226:227], v133, off
	v_lshl_add_u64 v[226:227], v[226:227], 0, s[56:57]
	v_mul_f32_e32 v228, 0xbfb8aa3b, v82
	v_exp_f32_e32 v228, v228
	s_nop 0
	v_add_f32_e32 v229, 1.0, v228
	v_div_scale_f32 v230, s[44:45], v229, v229, v82
	v_rcp_f32_e32 v231, v230
	v_div_scale_f32 v232, vcc, v82, v229, v82
	s_nop 0
	v_fma_f32 v131, -v230, v231, 1.0
	v_fmac_f32_e32 v231, v131, v231
	v_mul_f32_e32 v233, v232, v231
	v_fma_f32 v131, -v230, v233, v232
	v_fmac_f32_e32 v233, v131, v231
	v_fma_f32 v230, -v230, v233, v232
	v_div_fmas_f32 v230, v230, v231, v233
	v_div_fixup_f32 v135, v230, v229, v82
	v_mul_f32_e32 v135, v90, v135
	v_mul_f32_e32 v228, 0xbfb8aa3b, v86
	v_exp_f32_e32 v228, v228
	s_nop 0
	v_add_f32_e32 v229, 1.0, v228
	v_div_scale_f32 v230, s[44:45], v229, v229, v86
	v_rcp_f32_e32 v231, v230
	v_div_scale_f32 v232, vcc, v86, v229, v86
	s_nop 0
	v_fma_f32 v131, -v230, v231, 1.0
	v_fmac_f32_e32 v231, v131, v231
	v_mul_f32_e32 v233, v232, v231
	v_fma_f32 v131, -v230, v233, v232
	v_fmac_f32_e32 v233, v131, v231
	v_fma_f32 v230, -v230, v233, v232
	v_div_fmas_f32 v230, v230, v231, v233
	v_div_fixup_f32 v133, v230, v229, v86
	v_mul_f32_e32 v133, v94, v133
	v_cvt_pk_bf16_f32 v133, v135, v133
	global_store_dword v[226:227], v133, off
	v_lshl_add_u64 v[226:227], v[226:227], 0, s[56:57]
	v_mul_f32_e32 v228, 0xbfb8aa3b, v83
	v_exp_f32_e32 v228, v228
	s_nop 0
	v_add_f32_e32 v229, 1.0, v228
	v_div_scale_f32 v230, s[44:45], v229, v229, v83
	v_rcp_f32_e32 v231, v230
	v_div_scale_f32 v232, vcc, v83, v229, v83
	s_nop 0
	v_fma_f32 v131, -v230, v231, 1.0
	v_fmac_f32_e32 v231, v131, v231
	v_mul_f32_e32 v233, v232, v231
	v_fma_f32 v131, -v230, v233, v232
	v_fmac_f32_e32 v233, v131, v231
	v_fma_f32 v230, -v230, v233, v232
	v_div_fmas_f32 v230, v230, v231, v233
	v_div_fixup_f32 v135, v230, v229, v83
	v_mul_f32_e32 v135, v91, v135
	v_mul_f32_e32 v228, 0xbfb8aa3b, v87
	v_exp_f32_e32 v228, v228
	s_nop 0
	v_add_f32_e32 v229, 1.0, v228
	v_div_scale_f32 v230, s[44:45], v229, v229, v87
	v_rcp_f32_e32 v231, v230
	v_div_scale_f32 v232, vcc, v87, v229, v87
	s_nop 0
	v_fma_f32 v131, -v230, v231, 1.0
	v_fmac_f32_e32 v231, v131, v231
	v_mul_f32_e32 v233, v232, v231
	v_fma_f32 v131, -v230, v233, v232
	v_fmac_f32_e32 v233, v131, v231
	v_fma_f32 v230, -v230, v233, v232
	v_div_fmas_f32 v230, v230, v231, v233
	v_div_fixup_f32 v133, v230, v229, v87
	v_mul_f32_e32 v133, v95, v133
	v_cvt_pk_bf16_f32 v133, v135, v133
	global_store_dword v[226:227], v133, off
	v_lshl_add_u64 v[226:227], v[226:227], 0, s[40:41]
	v_mul_f32_e32 v228, 0xbfb8aa3b, v96
	v_exp_f32_e32 v228, v228
	s_nop 0
	v_add_f32_e32 v229, 1.0, v228
	v_div_scale_f32 v230, s[44:45], v229, v229, v96
	v_rcp_f32_e32 v231, v230
	v_div_scale_f32 v232, vcc, v96, v229, v96
	s_nop 0
	v_fma_f32 v131, -v230, v231, 1.0
	v_fmac_f32_e32 v231, v131, v231
	v_mul_f32_e32 v233, v232, v231
	v_fma_f32 v131, -v230, v233, v232
	v_fmac_f32_e32 v233, v131, v231
	v_fma_f32 v230, -v230, v233, v232
	v_div_fmas_f32 v230, v230, v231, v233
	v_div_fixup_f32 v135, v230, v229, v96
	v_mul_f32_e32 v135, v104, v135
	v_mul_f32_e32 v228, 0xbfb8aa3b, v100
	v_exp_f32_e32 v228, v228
	s_nop 0
	v_add_f32_e32 v229, 1.0, v228
	v_div_scale_f32 v230, s[44:45], v229, v229, v100
	v_rcp_f32_e32 v231, v230
	v_div_scale_f32 v232, vcc, v100, v229, v100
	s_nop 0
	v_fma_f32 v131, -v230, v231, 1.0
	v_fmac_f32_e32 v231, v131, v231
	v_mul_f32_e32 v233, v232, v231
	v_fma_f32 v131, -v230, v233, v232
	v_fmac_f32_e32 v233, v131, v231
	v_fma_f32 v230, -v230, v233, v232
	v_div_fmas_f32 v230, v230, v231, v233
	v_div_fixup_f32 v133, v230, v229, v100
	v_mul_f32_e32 v133, v108, v133
	v_cvt_pk_bf16_f32 v133, v135, v133
	global_store_dword v[226:227], v133, off
	v_lshl_add_u64 v[226:227], v[226:227], 0, s[56:57]
	v_mul_f32_e32 v228, 0xbfb8aa3b, v97
	v_exp_f32_e32 v228, v228
	s_nop 0
	v_add_f32_e32 v229, 1.0, v228
	v_div_scale_f32 v230, s[44:45], v229, v229, v97
	v_rcp_f32_e32 v231, v230
	v_div_scale_f32 v232, vcc, v97, v229, v97
	s_nop 0
	v_fma_f32 v131, -v230, v231, 1.0
	v_fmac_f32_e32 v231, v131, v231
	v_mul_f32_e32 v233, v232, v231
	v_fma_f32 v131, -v230, v233, v232
	v_fmac_f32_e32 v233, v131, v231
	v_fma_f32 v230, -v230, v233, v232
	v_div_fmas_f32 v230, v230, v231, v233
	v_div_fixup_f32 v135, v230, v229, v97
	v_mul_f32_e32 v135, v105, v135
	v_mul_f32_e32 v228, 0xbfb8aa3b, v101
	v_exp_f32_e32 v228, v228
	s_nop 0
	v_add_f32_e32 v229, 1.0, v228
	v_div_scale_f32 v230, s[44:45], v229, v229, v101
	v_rcp_f32_e32 v231, v230
	v_div_scale_f32 v232, vcc, v101, v229, v101
	s_nop 0
	v_fma_f32 v131, -v230, v231, 1.0
	v_fmac_f32_e32 v231, v131, v231
	v_mul_f32_e32 v233, v232, v231
	v_fma_f32 v131, -v230, v233, v232
	v_fmac_f32_e32 v233, v131, v231
	v_fma_f32 v230, -v230, v233, v232
	v_div_fmas_f32 v230, v230, v231, v233
	v_div_fixup_f32 v133, v230, v229, v101
	v_mul_f32_e32 v133, v109, v133
	v_cvt_pk_bf16_f32 v133, v135, v133
	global_store_dword v[226:227], v133, off
	v_lshl_add_u64 v[226:227], v[226:227], 0, s[56:57]
	v_mul_f32_e32 v228, 0xbfb8aa3b, v98
	v_exp_f32_e32 v228, v228
	s_nop 0
	v_add_f32_e32 v229, 1.0, v228
	v_div_scale_f32 v230, s[44:45], v229, v229, v98
	v_rcp_f32_e32 v231, v230
	v_div_scale_f32 v232, vcc, v98, v229, v98
	s_nop 0
	v_fma_f32 v131, -v230, v231, 1.0
	v_fmac_f32_e32 v231, v131, v231
	v_mul_f32_e32 v233, v232, v231
	v_fma_f32 v131, -v230, v233, v232
	v_fmac_f32_e32 v233, v131, v231
	v_fma_f32 v230, -v230, v233, v232
	v_div_fmas_f32 v230, v230, v231, v233
	v_div_fixup_f32 v135, v230, v229, v98
	v_mul_f32_e32 v135, v106, v135
	v_mul_f32_e32 v228, 0xbfb8aa3b, v102
	v_exp_f32_e32 v228, v228
	s_nop 0
	v_add_f32_e32 v229, 1.0, v228
	v_div_scale_f32 v230, s[44:45], v229, v229, v102
	v_rcp_f32_e32 v231, v230
	v_div_scale_f32 v232, vcc, v102, v229, v102
	s_nop 0
	v_fma_f32 v131, -v230, v231, 1.0
	v_fmac_f32_e32 v231, v131, v231
	v_mul_f32_e32 v233, v232, v231
	v_fma_f32 v131, -v230, v233, v232
	v_fmac_f32_e32 v233, v131, v231
	v_fma_f32 v230, -v230, v233, v232
	v_div_fmas_f32 v230, v230, v231, v233
	v_div_fixup_f32 v133, v230, v229, v102
	v_mul_f32_e32 v133, v110, v133
	v_cvt_pk_bf16_f32 v133, v135, v133
	global_store_dword v[226:227], v133, off
	v_lshl_add_u64 v[226:227], v[226:227], 0, s[56:57]
	v_mul_f32_e32 v228, 0xbfb8aa3b, v99
	v_exp_f32_e32 v228, v228
	s_nop 0
	v_add_f32_e32 v229, 1.0, v228
	v_div_scale_f32 v230, s[44:45], v229, v229, v99
	v_rcp_f32_e32 v231, v230
	v_div_scale_f32 v232, vcc, v99, v229, v99
	s_nop 0
	v_fma_f32 v131, -v230, v231, 1.0
	v_fmac_f32_e32 v231, v131, v231
	v_mul_f32_e32 v233, v232, v231
	v_fma_f32 v131, -v230, v233, v232
	v_fmac_f32_e32 v233, v131, v231
	v_fma_f32 v230, -v230, v233, v232
	v_div_fmas_f32 v230, v230, v231, v233
	v_div_fixup_f32 v135, v230, v229, v99
	v_mul_f32_e32 v135, v107, v135
	v_mul_f32_e32 v228, 0xbfb8aa3b, v103
	v_exp_f32_e32 v228, v228
	s_nop 0
	v_add_f32_e32 v229, 1.0, v228
	v_div_scale_f32 v230, s[44:45], v229, v229, v103
	v_rcp_f32_e32 v231, v230
	v_div_scale_f32 v232, vcc, v103, v229, v103
	s_nop 0
	v_fma_f32 v131, -v230, v231, 1.0
	v_fmac_f32_e32 v231, v131, v231
	v_mul_f32_e32 v233, v232, v231
	v_fma_f32 v131, -v230, v233, v232
	v_fmac_f32_e32 v233, v131, v231
	v_fma_f32 v230, -v230, v233, v232
	v_div_fmas_f32 v230, v230, v231, v233
	v_div_fixup_f32 v133, v230, v229, v103
	v_mul_f32_e32 v133, v111, v133
	v_cvt_pk_bf16_f32 v133, v135, v133
	global_store_dword v[226:227], v133, off
	v_lshl_add_u64 v[226:227], v[226:227], 0, s[40:41]
	v_mul_f32_e32 v228, 0xbfb8aa3b, v112
	v_exp_f32_e32 v228, v228
	s_nop 0
	v_add_f32_e32 v229, 1.0, v228
	v_div_scale_f32 v230, s[44:45], v229, v229, v112
	v_rcp_f32_e32 v231, v230
	v_div_scale_f32 v232, vcc, v112, v229, v112
	s_nop 0
	v_fma_f32 v131, -v230, v231, 1.0
	v_fmac_f32_e32 v231, v131, v231
	v_mul_f32_e32 v233, v232, v231
	v_fma_f32 v131, -v230, v233, v232
	v_fmac_f32_e32 v233, v131, v231
	v_fma_f32 v230, -v230, v233, v232
	v_div_fmas_f32 v230, v230, v231, v233
	v_div_fixup_f32 v135, v230, v229, v112
	v_mul_f32_e32 v135, v120, v135
	v_mul_f32_e32 v228, 0xbfb8aa3b, v116
	v_exp_f32_e32 v228, v228
	s_nop 0
	v_add_f32_e32 v229, 1.0, v228
	v_div_scale_f32 v230, s[44:45], v229, v229, v116
	v_rcp_f32_e32 v231, v230
	v_div_scale_f32 v232, vcc, v116, v229, v116
	s_nop 0
	v_fma_f32 v131, -v230, v231, 1.0
	v_fmac_f32_e32 v231, v131, v231
	v_mul_f32_e32 v233, v232, v231
	v_fma_f32 v131, -v230, v233, v232
	v_fmac_f32_e32 v233, v131, v231
	v_fma_f32 v230, -v230, v233, v232
	v_div_fmas_f32 v230, v230, v231, v233
	v_div_fixup_f32 v133, v230, v229, v116
	v_mul_f32_e32 v133, v124, v133
	v_cvt_pk_bf16_f32 v133, v135, v133
	global_store_dword v[226:227], v133, off
	v_lshl_add_u64 v[226:227], v[226:227], 0, s[56:57]
	v_mul_f32_e32 v228, 0xbfb8aa3b, v113
	v_exp_f32_e32 v228, v228
	s_nop 0
	v_add_f32_e32 v229, 1.0, v228
	v_div_scale_f32 v230, s[44:45], v229, v229, v113
	v_rcp_f32_e32 v231, v230
	v_div_scale_f32 v232, vcc, v113, v229, v113
	s_nop 0
	v_fma_f32 v131, -v230, v231, 1.0
	v_fmac_f32_e32 v231, v131, v231
	v_mul_f32_e32 v233, v232, v231
	v_fma_f32 v131, -v230, v233, v232
	v_fmac_f32_e32 v233, v131, v231
	v_fma_f32 v230, -v230, v233, v232
	v_div_fmas_f32 v230, v230, v231, v233
	v_div_fixup_f32 v135, v230, v229, v113
	v_mul_f32_e32 v135, v121, v135
	v_mul_f32_e32 v228, 0xbfb8aa3b, v117
	v_exp_f32_e32 v228, v228
	s_nop 0
	v_add_f32_e32 v229, 1.0, v228
	v_div_scale_f32 v230, s[44:45], v229, v229, v117
	v_rcp_f32_e32 v231, v230
	v_div_scale_f32 v232, vcc, v117, v229, v117
	s_nop 0
	v_fma_f32 v131, -v230, v231, 1.0
	v_fmac_f32_e32 v231, v131, v231
	v_mul_f32_e32 v233, v232, v231
	v_fma_f32 v131, -v230, v233, v232
	v_fmac_f32_e32 v233, v131, v231
	v_fma_f32 v230, -v230, v233, v232
	v_div_fmas_f32 v230, v230, v231, v233
	v_div_fixup_f32 v133, v230, v229, v117
	v_mul_f32_e32 v133, v125, v133
	v_cvt_pk_bf16_f32 v133, v135, v133
	global_store_dword v[226:227], v133, off
	v_lshl_add_u64 v[226:227], v[226:227], 0, s[56:57]
	v_mul_f32_e32 v228, 0xbfb8aa3b, v114
	v_exp_f32_e32 v228, v228
	s_nop 0
	v_add_f32_e32 v229, 1.0, v228
	v_div_scale_f32 v230, s[44:45], v229, v229, v114
	v_rcp_f32_e32 v231, v230
	v_div_scale_f32 v232, vcc, v114, v229, v114
	s_nop 0
	v_fma_f32 v131, -v230, v231, 1.0
	v_fmac_f32_e32 v231, v131, v231
	v_mul_f32_e32 v233, v232, v231
	v_fma_f32 v131, -v230, v233, v232
	v_fmac_f32_e32 v233, v131, v231
	v_fma_f32 v230, -v230, v233, v232
	v_div_fmas_f32 v230, v230, v231, v233
	v_div_fixup_f32 v135, v230, v229, v114
	v_mul_f32_e32 v135, v122, v135
	v_mul_f32_e32 v228, 0xbfb8aa3b, v118
	v_exp_f32_e32 v228, v228
	s_nop 0
	v_add_f32_e32 v229, 1.0, v228
	v_div_scale_f32 v230, s[44:45], v229, v229, v118
	v_rcp_f32_e32 v231, v230
	v_div_scale_f32 v232, vcc, v118, v229, v118
	s_nop 0
	v_fma_f32 v131, -v230, v231, 1.0
	v_fmac_f32_e32 v231, v131, v231
	v_mul_f32_e32 v233, v232, v231
	v_fma_f32 v131, -v230, v233, v232
	v_fmac_f32_e32 v233, v131, v231
	v_fma_f32 v230, -v230, v233, v232
	v_div_fmas_f32 v230, v230, v231, v233
	v_div_fixup_f32 v133, v230, v229, v118
	v_mul_f32_e32 v133, v126, v133
	v_cvt_pk_bf16_f32 v133, v135, v133
	global_store_dword v[226:227], v133, off
	v_lshl_add_u64 v[226:227], v[226:227], 0, s[56:57]
	v_mul_f32_e32 v228, 0xbfb8aa3b, v115
	v_exp_f32_e32 v228, v228
	s_nop 0
	v_add_f32_e32 v229, 1.0, v228
	v_div_scale_f32 v230, s[44:45], v229, v229, v115
	v_rcp_f32_e32 v231, v230
	v_div_scale_f32 v232, vcc, v115, v229, v115
	s_nop 0
	v_fma_f32 v131, -v230, v231, 1.0
	v_fmac_f32_e32 v231, v131, v231
	v_mul_f32_e32 v233, v232, v231
	v_fma_f32 v131, -v230, v233, v232
	v_fmac_f32_e32 v233, v131, v231
	v_fma_f32 v230, -v230, v233, v232
	v_div_fmas_f32 v230, v230, v231, v233
	v_div_fixup_f32 v135, v230, v229, v115
	v_mul_f32_e32 v135, v123, v135
	v_mul_f32_e32 v228, 0xbfb8aa3b, v119
	v_exp_f32_e32 v228, v228
	s_nop 0
	v_add_f32_e32 v229, 1.0, v228
	v_div_scale_f32 v230, s[44:45], v229, v229, v119
	v_rcp_f32_e32 v231, v230
	v_div_scale_f32 v232, vcc, v119, v229, v119
	s_nop 0
	v_fma_f32 v131, -v230, v231, 1.0
	v_fmac_f32_e32 v231, v131, v231
	v_mul_f32_e32 v233, v232, v231
	v_fma_f32 v131, -v230, v233, v232
	v_fmac_f32_e32 v233, v131, v231
	v_fma_f32 v230, -v230, v233, v232
	v_div_fmas_f32 v230, v230, v231, v233
	v_div_fixup_f32 v133, v230, v229, v119
	v_mul_f32_e32 v133, v127, v133
	v_cvt_pk_bf16_f32 v133, v135, v133
	global_store_dword v[226:227], v133, off
	v_readlane_b32 s55, v235, 33
	s_add_u32 s54, s54, s55
	s_branch .Lfi_tile
.Lfi_done:
	s_waitcnt vmcnt(0)
	s_branch .LBB0_1241

	.amdhsa_kernel _Z10fwd_kernel1Pii
		.amdhsa_group_segment_fixed_size 73748
		.amdhsa_private_segment_fixed_size 0
		.amdhsa_kernarg_size 608
		.amdhsa_user_sgpr_count 2
		.amdhsa_user_sgpr_dispatch_ptr 0
		.amdhsa_user_sgpr_queue_ptr 0
		.amdhsa_user_sgpr_kernarg_segment_ptr 1
		.amdhsa_user_sgpr_dispatch_id 0
		.amdhsa_user_sgpr_kernarg_preload_length 0
		.amdhsa_user_sgpr_kernarg_preload_offset 0
		.amdhsa_user_sgpr_private_segment_size 0
		.amdhsa_uses_dynamic_stack 0
		.amdhsa_enable_private_segment 0
		.amdhsa_system_sgpr_workgroup_id_x 1
		.amdhsa_system_sgpr_workgroup_id_y 0
		.amdhsa_system_sgpr_workgroup_id_z 0
		.amdhsa_system_sgpr_workgroup_info 0
		.amdhsa_system_vgpr_workitem_id 2
		.amdhsa_next_free_vgpr 256
		.amdhsa_next_free_sgpr 100
		.amdhsa_accum_offset 240
		.amdhsa_reserve_vcc 1
		.amdhsa_float_round_mode_32 0
		.amdhsa_float_round_mode_16_64 0
		.amdhsa_float_denorm_mode_32 3
		.amdhsa_float_denorm_mode_16_64 3
		.amdhsa_dx10_clamp 1
		.amdhsa_ieee_mode 1
		.amdhsa_fp16_overflow 0
		.amdhsa_tg_split 0
		.amdhsa_exception_fp_ieee_invalid_op 0
		.amdhsa_exception_fp_denorm_src 0
		.amdhsa_exception_fp_ieee_div_zero 0
		.amdhsa_exception_fp_ieee_overflow 0
		.amdhsa_exception_fp_ieee_underflow 0
		.amdhsa_exception_fp_ieee_inexact 0
		.amdhsa_exception_int_div_zero 0
	.end_amdhsa_kernel

amdhsa.kernels:
  - .agpr_count:     16
    .args:
      - .offset:         0
        .size:           344
        .value_kind:     by_value
      - .offset:         344
        .size:           4
        .value_kind:     by_value
      - .offset:         348
        .size:           4
        .value_kind:     by_value
      - .offset:         352
        .size:           4
        .value_kind:     hidden_block_count_x
      - .offset:         356
        .size:           4
        .value_kind:     hidden_block_count_y
      - .offset:         360
        .size:           4
        .value_kind:     hidden_block_count_z
      - .offset:         364
        .size:           2
        .value_kind:     hidden_group_size_x
      - .offset:         366
        .size:           2
        .value_kind:     hidden_group_size_y
      - .offset:         368
        .size:           2
        .value_kind:     hidden_group_size_z
      - .offset:         370
        .size:           2
        .value_kind:     hidden_remainder_x
      - .offset:         372
        .size:           2
        .value_kind:     hidden_remainder_y
      - .offset:         374
        .size:           2
        .value_kind:     hidden_remainder_z
      - .offset:         392
        .size:           8
        .value_kind:     hidden_global_offset_x
      - .offset:         400
        .size:           8
        .value_kind:     hidden_global_offset_y
      - .offset:         408
        .size:           8
        .value_kind:     hidden_global_offset_z
      - .offset:         416
        .size:           2
        .value_kind:     hidden_grid_dims
      - .offset:         440
        .size:           8
        .value_kind:     hidden_multigrid_sync_arg
    .group_segment_fixed_size: 73748
    .kernarg_segment_align: 8
    .kernarg_segment_size: 608
    .language:       OpenCL C
    .language_version:
      - 2
      - 0
    .max_flat_workgroup_size: 256
    .name:           _Z10fwd_kernel1Pii
    .private_segment_fixed_size: 0
    .sgpr_count:     106
    .sgpr_spill_count: 298
    .symbol:         _Z10fwd_kernel1Pii.kd
    .uniform_work_group_size: 1
    .uses_dynamic_stack: false
    .vgpr_count:     256
    .vgpr_spill_count: 0
    .wavefront_size: 64
